# st4 + sink logits fetched by an early vector load (lane = head) instead of a scalar load waited at the end of the SWA prologue
# speedup vs baseline: 1.0042x; 1.0042x over previous
.LBB0_176:
	s_and_b32 s0, s57, 7
	v_writelane_b32 v243, s57, 7
	s_ashr_i32 s1, s57, 3
	v_writelane_b32 v243, s0, 8
	s_lshl_b32 s0, s0, 12
	s_lshl_b32 s2, s1, 7
	v_mov_b32_e32 v36, v0
	s_add_i32 s20, s2, s0
	s_barrier
	v_readlane_b32 s94, v244, 20
	v_readlane_b32 s95, v244, 21
	v_and_b32_e32 v4, 63, v0
	v_lshlrev_b32_e32 v4, 2, v4
	s_nop 4
	global_load_dword v129, v4, s[94:95]
	v_readlane_b32 s90, v244, 18
	v_readlane_b32 s91, v244, 19
	s_nop 4
	global_load_dword v223, v4, s[90:91]
	v_readlane_b32 s94, v244, 22
	v_readlane_b32 s95, v244, 23
	v_and_b32_e32 v5, 3, v0
	v_lshlrev_b32_e32 v5, 2, v5
	s_nop 4
	global_load_dword v221, v5, s[94:95]
	s_cmp_gt_i32 s1, 0
	v_ashrrev_i32_e32 v50, 1, v36
	s_cselect_b64 s[22:23], -1, 0
	v_cmp_lt_i32_e32 vcc, s84, v50
	v_writelane_b32 v243, s1, 9
	s_or_b64 s[0:1], s[22:23], vcc
	v_and_b32_e32 v54, 1, v36
	v_writelane_b32 v243, s0, 10
	v_ashrrev_i32_e32 v51, 31, v50
	v_lshlrev_b32_e32 v2, 5, v54
	v_writelane_b32 v243, s1, 11
	s_xor_b64 s[0:1], s[0:1], -1
	s_and_saveexec_b64 s[4:5], s[0:1]
	s_xor_b64 s[0:1], exec, s[4:5]
	s_ashr_i32 s21, s20, 31
	v_lshl_add_u64 v[4:5], v[50:51], 0, s[20:21]
	v_lshlrev_b32_e32 v2, 5, v54
	v_mad_u64_u32 v[52:53], s[4:5], v4, s92, 0
	v_mad_i32_i24 v53, v5, s92, v53
	v_mov_b32_e32 v55, v2
	v_mov_b64_e32 v[48:49], v[2:3]
	s_or_saveexec_b64 s[0:1], s[0:1]
	v_mov_b32_e32 v110, 0
	s_mov_b32 s33, 0
	v_mov_b32_e32 v24, 0
	v_mov_b32_e32 v25, 0
	v_mov_b32_e32 v26, 0
	v_mov_b32_e32 v27, 0
	v_mov_b32_e32 v28, 0
	v_mov_b32_e32 v29, 0
	v_mov_b32_e32 v30, 0
	v_mov_b32_e32 v31, 0
	v_mov_b32_e32 v32, 0
	v_mov_b32_e32 v33, 0
	v_mov_b32_e32 v34, 0
	v_mov_b32_e32 v35, 0
	v_mov_b32_e32 v20, 0
	v_mov_b32_e32 v21, 0
	v_mov_b32_e32 v22, 0
	v_mov_b32_e32 v23, 0
	v_mov_b32_e32 v4, 0
	v_mov_b32_e32 v5, 0
	v_mov_b32_e32 v6, 0
	v_mov_b32_e32 v7, 0
	v_mov_b32_e32 v12, 0
	v_mov_b32_e32 v13, 0
	v_mov_b32_e32 v14, 0
	v_mov_b32_e32 v15, 0
	v_mov_b32_e32 v8, 0
	v_mov_b32_e32 v9, 0
	v_mov_b32_e32 v10, 0
	v_mov_b32_e32 v11, 0
	v_mov_b32_e32 v16, 0
	v_mov_b32_e32 v17, 0
	v_mov_b32_e32 v18, 0
	v_mov_b32_e32 v19, 0
	s_xor_b64 exec, exec, s[0:1]
	s_cbranch_execz .LBB0_180
	s_ashr_i32 s21, s20, 31
	v_lshl_add_u64 v[38:39], v[50:51], 0, s[20:21]
	v_mov_b64_e32 v[4:5], s[88:89]
	v_mad_u64_u32 v[4:5], s[4:5], v38, s92, v[4:5]
	v_mad_i32_i24 v5, v39, s92, v5
	v_lshlrev_b32_e32 v6, 6, v54
	v_mov_b32_e32 v7, v3
	s_mov_b32 s4, 0xfff70b00
	v_lshl_add_u64 v[4:5], v[4:5], 0, v[6:7]
	s_mov_b32 s5, -1
	v_lshl_add_u64 v[20:21], v[4:5], 0, s[4:5]
	s_mov_b32 s4, 0xfff70a00
	s_mov_b32 s3, 0xfff71000
	s_mov_b32 s5, -1
	v_add_co_u32_e32 v14, vcc, s3, v4
	v_lshl_add_u64 v[12:13], v[4:5], 0, s[4:5]
	s_nop 0
	v_addc_co_u32_e32 v15, vcc, -1, v5, vcc
	global_load_dwordx4 v[8:11], v[12:13], off offset:32
	global_load_dwordx4 v[16:19], v[12:13], off offset:48
	global_load_dwordx4 v[4:7], v[14:15], off offset:-1536
	global_load_dwordx4 v[24:27], v[14:15], off offset:-1280
	global_load_dwordx4 v[28:31], v[20:21], off offset:16
	global_load_dwordx4 v[32:35], v[20:21], off offset:32
	s_nop 0
	global_load_dwordx4 v[12:15], v[12:13], off offset:16
	s_nop 0
	global_load_dwordx4 v[20:23], v[20:21], off offset:48
	v_mad_u64_u32 v[52:53], s[4:5], v38, s92, 0
	v_mad_i32_i24 v53, v39, s92, v53
	v_mov_b64_e32 v[48:49], v[2:3]
	v_mov_b32_e32 v55, v2
.LBB0_180:
	s_or_b64 exec, exec, s[0:1]
	v_and_b32_e32 v37, 64, v182
	v_ashrrev_i32_e32 v59, 6, v36
	v_bfe_u32 v51, v36, 4, 2
	v_and_b32_e32 v56, 15, v36
	v_xor_b32_e32 v36, 1, v182
	v_add_u32_e32 v37, 64, v37
	v_cmp_lt_i32_e32 vcc, v36, v37
	v_lshlrev_b32_e32 v2, 4, v59
	v_min_i32_e32 v57, 6, v59
	v_and_b32_e32 v57, -2, v57
	v_cndmask_b32_e32 v61, v182, v36, vcc
	v_xor_b32_e32 v36, 16, v182
	v_cmp_lt_i32_e32 vcc, v36, v37
	v_lshlrev_b32_e32 v111, 2, v51
	v_lshlrev_b32_e32 v68, 4, v57
	v_cndmask_b32_e32 v66, v182, v36, vcc
	v_xor_b32_e32 v36, 32, v182
	v_cmp_lt_i32_e32 vcc, v36, v37
	v_or_b32_e32 v38, v68, v111
	s_movk_i32 s3, 0x7e
	v_cndmask_b32_e32 v67, v182, v36, vcc
	v_cmp_eq_u32_e32 vcc, 1, v51
	v_or_b32_e32 v39, 2, v38
	v_add_u32_e32 v69, 16, v68
	v_cndmask_b32_e64 v36, 0, 1.0, vcc
	v_cmp_ne_u32_e32 vcc, 0, v51
	v_add_u32_e32 v70, 2, v57
	v_lshlrev_b32_e32 v71, 4, v70
	v_cndmask_b32_e32 v114, -1.0, v36, vcc
	v_or_b32_e32 v36, v2, v56
	v_add_u32_e32 v37, 0x80, v36
	v_cmp_gt_i32_e32 vcc, v38, v36
	v_cmp_le_i32_e64 s[0:1], v38, v37
	s_and_b64 s[0:1], vcc, s[0:1]
	v_cmp_lt_i32_e32 vcc, s84, v38
	s_or_b64 s[4:5], s[22:23], vcc
	s_and_b64 s[0:1], s[0:1], s[4:5]
	v_cmp_ge_i32_e32 vcc, v38, v36
	v_cmp_lt_i32_e64 s[4:5], v38, v37
	s_and_b64 s[4:5], vcc, s[4:5]
	v_cmp_lt_i32_e32 vcc, s3, v38
	v_writelane_b32 v243, s0, 12
	s_or_b64 s[6:7], s[22:23], vcc
	v_cmp_gt_i32_e32 vcc, v39, v36
	v_writelane_b32 v243, s1, 13
	s_and_b64 s[0:1], s[4:5], s[6:7]
	v_cmp_le_i32_e64 s[6:7], v39, v37
	s_and_b64 s[6:7], vcc, s[6:7]
	v_cmp_lt_i32_e32 vcc, s84, v39
	v_writelane_b32 v243, s0, 14
	s_or_b64 s[8:9], s[22:23], vcc
	v_or_b32_e32 v38, 3, v38
	v_writelane_b32 v243, s1, 15
	s_and_b64 s[0:1], s[6:7], s[8:9]
	v_cmp_gt_i32_e32 vcc, v38, v36
	v_cmp_le_i32_e64 s[8:9], v38, v37
	s_and_b64 s[8:9], vcc, s[8:9]
	v_cmp_lt_i32_e32 vcc, s84, v38
	v_writelane_b32 v243, s0, 16
	s_or_b64 s[10:11], s[22:23], vcc
	v_or_b32_e32 v38, v69, v111
	v_writelane_b32 v243, s1, 17
	s_and_b64 s[0:1], s[8:9], s[10:11]
	v_cmp_gt_i32_e32 vcc, v38, v36
	v_cmp_le_i32_e64 s[10:11], v38, v37
	s_and_b64 s[10:11], vcc, s[10:11]
	v_cmp_lt_i32_e32 vcc, s84, v38
	v_writelane_b32 v243, s0, 18
	s_or_b64 s[12:13], s[22:23], vcc
	v_cmp_ge_i32_e32 vcc, v38, v36
	v_writelane_b32 v243, s1, 19
	s_and_b64 s[0:1], s[10:11], s[12:13]
	v_cmp_lt_i32_e64 s[12:13], v38, v37
	s_and_b64 s[12:13], vcc, s[12:13]
	v_cmp_lt_i32_e32 vcc, s3, v38
	v_writelane_b32 v243, s0, 20
	s_or_b64 s[14:15], s[22:23], vcc
	v_or_b32_e32 v39, 2, v38
	v_writelane_b32 v243, s1, 21
	s_and_b64 s[0:1], s[12:13], s[14:15]
	v_cmp_gt_i32_e32 vcc, v39, v36
	v_cmp_le_i32_e64 s[14:15], v39, v37
	s_and_b64 s[14:15], vcc, s[14:15]
	v_cmp_lt_i32_e32 vcc, s84, v39
	v_writelane_b32 v243, s0, 22
	s_or_b64 s[16:17], s[22:23], vcc
	v_or_b32_e32 v38, 3, v38
	v_writelane_b32 v243, s1, 23
	s_and_b64 s[0:1], s[14:15], s[16:17]
	v_cmp_gt_i32_e32 vcc, v38, v36
	v_cmp_le_i32_e64 s[16:17], v38, v37
	s_and_b64 s[16:17], vcc, s[16:17]
	v_cmp_lt_i32_e32 vcc, s84, v38
	v_writelane_b32 v243, s0, 24
	s_or_b64 s[18:19], s[22:23], vcc
	v_or_b32_e32 v38, v71, v111
	v_writelane_b32 v243, s1, 25
	s_and_b64 s[0:1], s[16:17], s[18:19]
	v_cmp_gt_i32_e32 vcc, v38, v36
	v_cmp_le_i32_e64 s[18:19], v38, v37
	s_and_b64 s[18:19], vcc, s[18:19]
	v_cmp_lt_i32_e32 vcc, s84, v38
	v_writelane_b32 v243, s0, 26
	s_mov_b32 s4, s20
	s_or_b64 s[20:21], s[22:23], vcc
	v_writelane_b32 v243, s1, 27
	s_and_b64 s[0:1], s[18:19], s[20:21]
	v_cmp_ge_i32_e32 vcc, v38, v36
	v_cmp_lt_i32_e64 s[20:21], v38, v37
	s_and_b64 s[20:21], vcc, s[20:21]
	v_cmp_lt_i32_e32 vcc, s3, v38
	s_mov_b64 s[6:7], s[22:23]
	s_or_b64 s[22:23], s[22:23], vcc
	v_or_b32_e32 v39, 2, v38
	s_and_b64 s[20:21], s[20:21], s[22:23]
	v_cmp_gt_i32_e32 vcc, v39, v36
	v_cmp_le_i32_e64 s[22:23], v39, v37
	s_and_b64 s[22:23], vcc, s[22:23]
	v_cmp_lt_i32_e32 vcc, s84, v39
	s_or_b64 s[24:25], s[6:7], vcc
	v_or_b32_e32 v38, 3, v38
	s_and_b64 s[22:23], s[22:23], s[24:25]
	v_cmp_gt_i32_e32 vcc, v38, v36
	v_cmp_le_i32_e64 s[24:25], v38, v37
	v_add_u32_e32 v72, 48, v68
	s_and_b64 s[24:25], vcc, s[24:25]
	v_cmp_lt_i32_e32 vcc, s84, v38
	s_or_b64 s[26:27], s[6:7], vcc
	v_or_b32_e32 v38, v72, v111
	s_and_b64 s[24:25], s[24:25], s[26:27]
	v_cmp_gt_i32_e32 vcc, v38, v36
	v_cmp_le_i32_e64 s[26:27], v38, v37
	s_and_b64 s[26:27], vcc, s[26:27]
	v_cmp_lt_i32_e32 vcc, s84, v38
	s_or_b64 s[28:29], s[6:7], vcc
	s_and_b64 s[26:27], s[26:27], s[28:29]
	v_cmp_ge_i32_e32 vcc, v38, v36
	v_cmp_lt_i32_e64 s[28:29], v38, v37
	s_and_b64 s[28:29], vcc, s[28:29]
	v_cmp_lt_i32_e32 vcc, s3, v38
	s_or_b64 s[30:31], s[6:7], vcc
	v_or_b32_e32 v39, 2, v38
	s_and_b64 s[28:29], s[28:29], s[30:31]
	v_cmp_gt_i32_e32 vcc, v39, v36
	v_cmp_le_i32_e64 s[30:31], v39, v37
	s_and_b64 s[30:31], vcc, s[30:31]
	v_cmp_lt_i32_e32 vcc, s84, v39
	s_or_b64 s[34:35], s[6:7], vcc
	v_or_b32_e32 v38, 3, v38
	v_add_u32_e32 v73, 4, v57
	s_and_b64 s[30:31], s[30:31], s[34:35]
	v_cmp_gt_i32_e32 vcc, v38, v36
	v_cmp_le_i32_e64 s[34:35], v38, v37
	v_lshlrev_b32_e32 v74, 4, v73
	s_and_b64 s[34:35], vcc, s[34:35]
	v_cmp_lt_i32_e32 vcc, s84, v38
	s_or_b64 s[36:37], s[6:7], vcc
	v_or_b32_e32 v38, v74, v111
	s_and_b64 s[34:35], s[34:35], s[36:37]
	v_cmp_gt_i32_e32 vcc, v38, v36
	v_cmp_le_i32_e64 s[36:37], v38, v37
	s_and_b64 s[36:37], vcc, s[36:37]
	v_cmp_lt_i32_e32 vcc, s84, v38
	s_or_b64 s[38:39], s[6:7], vcc
	s_and_b64 s[36:37], s[36:37], s[38:39]
	v_cmp_ge_i32_e32 vcc, v38, v36
	v_cmp_lt_i32_e64 s[38:39], v38, v37
	s_and_b64 s[38:39], vcc, s[38:39]
	v_cmp_lt_i32_e32 vcc, s3, v38
	s_or_b64 s[40:41], s[6:7], vcc
	v_or_b32_e32 v39, 2, v38
	s_and_b64 s[38:39], s[38:39], s[40:41]
	v_cmp_gt_i32_e32 vcc, v39, v36
	v_cmp_le_i32_e64 s[40:41], v39, v37
	s_and_b64 s[40:41], vcc, s[40:41]
	v_cmp_lt_i32_e32 vcc, s84, v39
	s_or_b64 s[42:43], s[6:7], vcc
	v_or_b32_e32 v38, 3, v38
	s_and_b64 s[40:41], s[40:41], s[42:43]
	v_cmp_gt_i32_e32 vcc, v38, v36
	v_cmp_le_i32_e64 s[42:43], v38, v37
	v_add_u32_e32 v75, 0x50, v68
	s_and_b64 s[42:43], vcc, s[42:43]
	v_cmp_lt_i32_e32 vcc, s84, v38
	s_or_b64 s[44:45], s[6:7], vcc
	v_or_b32_e32 v38, v75, v111
	s_and_b64 s[42:43], s[42:43], s[44:45]
	v_cmp_gt_i32_e32 vcc, v38, v36
	v_cmp_le_i32_e64 s[44:45], v38, v37
	s_and_b64 s[44:45], vcc, s[44:45]
	v_cmp_lt_i32_e32 vcc, s84, v38
	s_or_b64 s[46:47], s[6:7], vcc
	s_and_b64 s[44:45], s[44:45], s[46:47]
	v_cmp_ge_i32_e32 vcc, v38, v36
	v_cmp_lt_i32_e64 s[46:47], v38, v37
	s_and_b64 s[46:47], vcc, s[46:47]
	v_cmp_lt_i32_e32 vcc, s3, v38
	s_or_b64 s[48:49], s[6:7], vcc
	v_or_b32_e32 v39, 2, v38
	s_and_b64 s[46:47], s[46:47], s[48:49]
	v_cmp_gt_i32_e32 vcc, v39, v36
	v_cmp_le_i32_e64 s[48:49], v39, v37
	s_and_b64 s[48:49], vcc, s[48:49]
	v_cmp_lt_i32_e32 vcc, s84, v39
	s_or_b64 s[50:51], s[6:7], vcc
	v_or_b32_e32 v38, 3, v38
	v_add_u32_e32 v76, 6, v57
	s_and_b64 s[48:49], s[48:49], s[50:51]
	v_cmp_gt_i32_e32 vcc, v38, v36
	v_cmp_le_i32_e64 s[50:51], v38, v37
	v_lshlrev_b32_e32 v77, 4, v76
	s_and_b64 s[50:51], vcc, s[50:51]
	v_cmp_lt_i32_e32 vcc, s84, v38
	s_or_b64 s[52:53], s[6:7], vcc
	v_or_b32_e32 v38, v77, v111
	s_and_b64 s[50:51], s[50:51], s[52:53]
	v_cmp_gt_i32_e32 vcc, v38, v36
	v_cmp_le_i32_e64 s[52:53], v38, v37
	s_and_b64 s[52:53], vcc, s[52:53]
	v_cmp_lt_i32_e32 vcc, s84, v38
	s_or_b64 s[54:55], s[6:7], vcc
	s_and_b64 s[52:53], s[52:53], s[54:55]
	v_cmp_ge_i32_e32 vcc, v38, v36
	v_cmp_lt_i32_e64 s[54:55], v38, v37
	s_and_b64 s[54:55], vcc, s[54:55]
	v_cmp_lt_i32_e32 vcc, s3, v38
	s_or_b64 s[56:57], s[6:7], vcc
	v_or_b32_e32 v39, 2, v38
	s_and_b64 s[54:55], s[54:55], s[56:57]
	v_cmp_gt_i32_e32 vcc, v39, v36
	v_cmp_le_i32_e64 s[56:57], v39, v37
	s_and_b64 s[56:57], vcc, s[56:57]
	v_cmp_lt_i32_e32 vcc, s84, v39
	s_or_b64 s[58:59], s[6:7], vcc
	v_or_b32_e32 v38, 3, v38
	s_and_b64 s[56:57], s[56:57], s[58:59]
	v_cmp_gt_i32_e32 vcc, v38, v36
	v_cmp_le_i32_e64 s[58:59], v38, v37
	v_add_u32_e32 v78, 0x70, v68
	s_and_b64 s[58:59], vcc, s[58:59]
	v_cmp_lt_i32_e32 vcc, s84, v38
	s_or_b64 s[60:61], s[6:7], vcc
	v_or_b32_e32 v38, v78, v111
	s_and_b64 s[58:59], s[58:59], s[60:61]
	v_cmp_gt_i32_e32 vcc, v38, v36
	v_cmp_le_i32_e64 s[60:61], v38, v37
	s_and_b64 s[60:61], vcc, s[60:61]
	v_cmp_lt_i32_e32 vcc, s84, v38
	s_or_b64 s[62:63], s[6:7], vcc
	s_and_b64 s[60:61], s[60:61], s[62:63]
	v_cmp_ge_i32_e32 vcc, v38, v36
	v_cmp_lt_i32_e64 s[62:63], v38, v37
	s_and_b64 s[62:63], vcc, s[62:63]
	v_cmp_lt_i32_e32 vcc, s3, v38
	s_or_b64 s[64:65], s[6:7], vcc
	v_or_b32_e32 v39, 2, v38
	s_and_b64 s[62:63], s[62:63], s[64:65]
	v_cmp_gt_i32_e32 vcc, v39, v36
	v_cmp_le_i32_e64 s[64:65], v39, v37
	s_and_b64 s[64:65], vcc, s[64:65]
	v_cmp_lt_i32_e32 vcc, s84, v39
	s_or_b64 s[66:67], s[6:7], vcc
	v_or_b32_e32 v38, 3, v38
	s_and_b64 s[64:65], s[64:65], s[66:67]
	v_cmp_gt_i32_e32 vcc, v38, v36
	v_cmp_le_i32_e64 s[66:67], v38, v37
	v_add_u32_e32 v79, 8, v57
	s_and_b64 s[66:67], vcc, s[66:67]
	v_cmp_lt_i32_e32 vcc, s84, v38
	v_lshlrev_b32_e32 v98, 4, v79
	s_or_b64 s[68:69], s[6:7], vcc
	v_or_b32_e32 v38, v98, v111
	s_and_b64 s[66:67], s[66:67], s[68:69]
	v_cmp_gt_i32_e32 vcc, v38, v36
	v_cmp_le_i32_e64 s[68:69], v38, v37
	s_and_b64 s[68:69], vcc, s[68:69]
	v_cmp_lt_i32_e32 vcc, s84, v38
	s_or_b64 s[70:71], s[6:7], vcc
	s_and_b64 s[68:69], s[68:69], s[70:71]
	v_cmp_ge_i32_e32 vcc, v38, v36
	v_cmp_lt_i32_e64 s[70:71], v38, v37
	s_and_b64 s[70:71], vcc, s[70:71]
	v_cmp_lt_i32_e32 vcc, s3, v38
	s_or_b64 s[72:73], s[6:7], vcc
	v_or_b32_e32 v39, 2, v38
	s_and_b64 s[70:71], s[70:71], s[72:73]
	v_cmp_gt_i32_e32 vcc, v39, v36
	v_cmp_le_i32_e64 s[72:73], v39, v37
	s_and_b64 s[72:73], vcc, s[72:73]
	v_cmp_lt_i32_e32 vcc, s84, v39
	s_or_b64 s[74:75], s[6:7], vcc
	v_or_b32_e32 v38, 3, v38
	s_and_b64 s[72:73], s[72:73], s[74:75]
	v_cmp_gt_i32_e32 vcc, v38, v36
	v_cmp_le_i32_e64 s[74:75], v38, v37
	s_and_b64 s[74:75], vcc, s[74:75]
	v_cmp_lt_i32_e32 vcc, s84, v38
	v_add_u32_e32 v99, 0x90, v68
	s_or_b64 s[76:77], s[6:7], vcc
	v_or_b32_e32 v38, v99, v111
	s_and_b64 s[74:75], s[74:75], s[76:77]
	v_cmp_gt_i32_e32 vcc, v38, v36
	v_cmp_le_i32_e64 s[76:77], v38, v37
	s_and_b64 s[76:77], vcc, s[76:77]
	v_cmp_lt_i32_e32 vcc, s84, v38
	s_or_b64 s[78:79], s[6:7], vcc
	s_and_b64 s[76:77], s[76:77], s[78:79]
	v_cmp_ge_i32_e32 vcc, v38, v36
	v_cmp_lt_i32_e64 s[78:79], v38, v37
	s_and_b64 s[78:79], vcc, s[78:79]
	v_cmp_lt_i32_e32 vcc, s3, v38
	s_or_b64 s[80:81], s[6:7], vcc
	v_or_b32_e32 v39, 2, v38
	s_and_b64 s[78:79], s[78:79], s[80:81]
	v_cmp_gt_i32_e32 vcc, v39, v36
	v_cmp_le_i32_e64 s[80:81], v39, v37
	s_and_b64 s[80:81], vcc, s[80:81]
	v_cmp_lt_i32_e32 vcc, s84, v39
	s_or_b64 s[82:83], s[6:7], vcc
	v_writelane_b32 v243, s6, 28
	v_or_b32_e32 v38, 3, v38
	v_add_u32_e32 v64, s2, v50
	v_writelane_b32 v243, s7, 29
	v_add_u32_e32 v90, s2, v2
	s_mov_b32 s2, s4
	v_add_u32_e32 v2, s4, v2
	s_and_b64 s[80:81], s[80:81], s[82:83]
	v_cmp_gt_i32_e32 vcc, v38, v36
	v_cmp_le_i32_e64 s[82:83], v38, v37
	v_writelane_b32 v243, s2, 30
	v_or_b32_e32 v80, v2, v56
	v_lshlrev_b32_e32 v58, 3, v51
	v_mov_b64_e32 v[36:37], s[88:89]
	v_writelane_b32 v243, s3, 31
	v_mad_i64_i32 v[82:83], s[2:3], v80, s92, v[36:37]
	v_lshlrev_b32_e32 v2, 4, v51
	v_bitop3_b32 v60, v58, 8, v58 bitop3:0xc
	v_lshl_add_u64 v[36:37], v[82:83], 0, v[2:3]
	v_lshlrev_b32_e32 v44, 1, v60
	v_mov_b32_e32 v45, v3
	s_and_b64 s[82:83], vcc, s[82:83]
	v_cmp_lt_i32_e32 vcc, s84, v38
	global_load_dwordx4 v[40:43], v[36:37], off offset:2048
	s_nop 0
	global_load_dwordx4 v[36:39], v[36:37], off offset:2112
	v_lshl_add_u64 v[44:45], v[82:83], 0, v[44:45]
	global_load_dwordx4 v[44:47], v[44:45], off offset:2048
	v_mul_lo_u32 v59, v59, s93
	v_add_u32_e32 v59, s96, v59
	v_mul_u32_u24_e32 v100, 0x210, v56
	v_add3_u32 v109, v59, v100, v58
	v_mul_lo_u32 v59, v50, s97
	v_add_u32_e32 v62, 0, v59
	v_lshl_add_u32 v115, v55, 1, v62
	v_mad_u64_u32 v[62:63], s[2:3], v50, s98, v[62:63]
	v_lshl_add_u64 v[52:53], s[88:89], 0, v[52:53]
	s_mov_b32 s2, 0xfff70b80
	v_lshl_add_u64 v[52:53], v[48:49], 1, v[52:53]
	s_mov_b32 s3, -1
	v_lshl_add_u64 v[86:87], v[52:53], 0, s[2:3]
	s_mov_b32 s2, 0xfff70a80
	s_mov_b32 s3, -1
	v_max_i32_e32 v50, 0x80, v64
	v_lshl_add_u64 v[88:89], v[52:53], 0, s[2:3]
	v_or_b32_e32 v52, v90, v56
	v_lshl_add_u32 v64, v50, 4, v183
	v_lshlrev_b32_e32 v52, 4, v52
	s_or_b64 s[84:85], s[6:7], vcc
	v_ashrrev_i32_e32 v65, 31, v64
	v_ashrrev_i32_e32 v53, 31, v52
	s_and_b64 s[82:83], s[82:83], s[84:85]
	v_lshl_add_u64 v[84:85], v[64:65], 2, s[86:87]
	v_lshl_add_u64 v[90:91], v[52:53], 2, s[86:87]
	s_mov_b32 s2, s96
	v_readlane_b32 s84, v244, 10
	v_readlane_b32 s88, v244, 14
	v_readlane_b32 s89, v244, 15
	v_readlane_b32 s90, v244, 16
	v_readlane_b32 s91, v244, 17
	v_readlane_b32 s92, v244, 18
	v_readlane_b32 s93, v244, 19
	v_readlane_b32 s94, v244, 20
	v_readlane_b32 s95, v244, 21
	v_readlane_b32 s96, v244, 22
	v_readlane_b32 s97, v244, 23
	s_mov_b64 s[8:9], s[88:89]
	v_add_u32_e32 v52, 0, v2
	s_mov_b64 s[12:13], s[92:93]
	v_lshlrev_b32_e32 v2, 5, v51
	v_lshl_add_u64 v[94:95], s[12:13], 0, v[2:3]
	v_lshlrev_b32_e32 v2, 2, v60
	s_mov_b64 s[10:11], s[90:91]
	s_mov_b64 s[14:15], s[94:95]
	s_mov_b64 s[16:17], s[96:97]
	s_movk_i32 s97, 0x90
	v_add_u32_e32 v96, 0x21e00, v2
	v_or_b32_e32 v2, v68, v56
	v_lshlrev_b32_e32 v92, 2, v48
	v_add_u32_e32 v92, 0x21d00, v92
	v_mul_lo_u32 v48, v2, s97
	v_or_b32_e32 v2, v69, v56
	v_mul_lo_u32 v49, v2, s97
	v_or_b32_e32 v2, v71, v56
	v_mul_lo_u32 v55, v2, s97
	v_or_b32_e32 v2, v72, v56
	v_mul_lo_u32 v59, v2, s97
	v_or_b32_e32 v2, v74, v56
	v_mul_lo_u32 v61, v2, s97
	v_or_b32_e32 v2, v75, v56
	v_mul_lo_u32 v63, v2, s97
	v_or_b32_e32 v2, v77, v56
	v_mul_lo_u32 v64, v2, s97
	v_or_b32_e32 v2, v78, v56
	v_mul_lo_u32 v65, v2, s97
	v_or_b32_e32 v2, v98, v56
	v_lshlrev_b32_e32 v128, 2, v66
	v_mov_b32_e32 v53, v52
	v_mul_lo_u32 v66, v2, s97
	v_or_b32_e32 v2, v99, v56
	v_mul_u32_u24_e32 v50, 0x4200, v54
	v_lshlrev_b32_e32 v113, 2, v67
	v_readlane_b32 s85, v244, 11
	v_readlane_b32 s86, v244, 12
	v_readlane_b32 s87, v244, 13
	v_readlane_b32 s98, v244, 24
	v_mul_lo_u32 v56, v2, s97
	v_lshl_add_u32 v57, v57, 5, v53
	v_lshl_add_u32 v67, v70, 5, v53
	v_lshl_add_u32 v68, v73, 5, v53
	v_lshl_add_u32 v69, v76, 5, v53
	v_lshl_add_u32 v53, v79, 5, v53
	v_ashrrev_i32_e32 v81, 31, v80
	v_readlane_b32 s99, v244, 25
	s_movk_i32 s98, 0xff72
	s_mov_b32 s96, s2
	s_movk_i32 s93, 0x2100
	s_movk_i32 s92, 0x1200
	v_and_b32_e32 v241, 24, v62
	v_and_b32_e32 v242, 32, v62
	v_and_b32_e32 v62, 0xffffffc7, v62
	v_lshlrev_b32_e32 v241, 1, v241
	v_lshrrev_b32_e32 v242, 2, v242
	v_or3_b32 v62, v62, v241, v242
	v_add_u32_e32 v116, v62, v50
	v_lshlrev_b32_e32 v2, 1, v60
	v_lshlrev_b32_e32 v98, 1, v58
	v_add_u32_e32 v117, v52, v48
	v_add_u32_e32 v118, v52, v49
	v_add_u32_e32 v119, v52, v55
	v_add_u32_e32 v120, v52, v59
	v_add_u32_e32 v121, v52, v61
	v_add_u32_e32 v122, v52, v63
	v_add_u32_e32 v123, v52, v64
	v_add_u32_e32 v124, v52, v65
	v_add_u32_e32 v125, v52, v66
	v_add_u32_e32 v126, v52, v56
	v_add_u32_e32 v127, v57, v100
	v_add_u32_e32 v130, v67, v100
	v_add_u32_e32 v131, v68, v100
	v_add_u32_e32 v132, v69, v100
	v_add_u32_e32 v133, v53, v100
	v_cmp_eq_u32_e64 s[84:85], 0, v54
	v_cmp_gt_u32_e64 s[86:87], 2, v51
	global_load_dwordx4 v[224:227], v[94:95], off
	global_load_dwordx4 v[228:231], v[94:95], off offset:16
	global_load_dwordx4 v[232:235], v[94:95], off offset:128
	global_load_dwordx4 v[236:239], v[94:95], off offset:144
	global_load_dwordx4 v[248:251], v[90:91], off offset:32
	global_load_dwordx4 v[252:255], v[90:91], off offset:48
	v_mov_b32_e32 v240, 1.0
	v_mov_b32_e32 v241, 1.0
	v_mov_b32_e32 v242, 1.0
	v_mov_b32_e32 v245, 1.0
	v_mov_b32_e32 v246, 1.0
	v_mov_b32_e32 v247, 1.0
	v_mov_b32_e32 v217, 1.0
	v_mov_b32_e32 v219, 1.0
	s_and_saveexec_b64 vcc, s[86:87]
	global_load_dword v240, v[90:91], off
	global_load_dword v241, v[90:91], off offset:4
	global_load_dword v242, v[90:91], off offset:8
	global_load_dword v245, v[90:91], off offset:12
	global_load_dword v246, v[90:91], off offset:16
	global_load_dword v247, v[90:91], off offset:20
	global_load_dword v217, v[90:91], off offset:24
	global_load_dword v219, v[90:91], off offset:28
	s_or_b64 exec, exec, vcc
	s_waitcnt vmcnt(17)
	v_and_b32_e32 v90, 63, v0
	v_lshlrev_b32_e32 v90, 2, v90
	v_add_u32_e32 v90, 0x21d00, v90
	ds_write_b32 v90, v129
	ds_write_b32 v90, v223 offset:256
	s_waitcnt lgkmcnt(0)
	s_mov_b64 s[2:3], -1
	s_branch .LBB0_182

.LBB0_189:
	v_readlane_b32 s4, v244, 10
	s_xor_b64 s[2:3], s[2:3], -1
	s_lshl_b64 s[94:95], s[90:91], 2
	v_readlane_b32 s16, v244, 22
	v_readlane_b32 s17, v244, 23
	s_add_u32 s94, s16, s94
	s_addc_u32 s95, s17, s95
	ds_read_b128 v[134:137], v117
	ds_read_b128 v[138:141], v117 offset:64
	s_nop 0
	v_readlane_b32 s94, v221, s90
	ds_read_b128 v[142:145], v118
	ds_read_b128 v[146:149], v118 offset:64
	s_waitcnt lgkmcnt(3)
	v_mfma_f32_16x16x32_bf16 v[134:137], v[134:137], v[72:75], 0
	v_readlane_b32 s6, v244, 12
	v_readlane_b32 s7, v244, 13
	s_mov_b32 s4, 0xf149f2ca
	s_waitcnt lgkmcnt(1)
	v_mfma_f32_16x16x32_bf16 v[142:145], v[142:145], v[72:75], 0
	v_readlane_b32 s6, v243, 12
	v_mov_b32_e32 v100, s4
	v_readlane_b32 s7, v243, 13
	v_mfma_f32_16x16x32_bf16 v[134:137], v[138:141], v[68:71], v[134:137]
	ds_read_b128 v[138:141], v119
	v_mov_b32_e32 v178, s4
	v_mov_b32_e32 v216, s4
	s_waitcnt lgkmcnt(1)
	v_mfma_f32_16x16x32_bf16 v[142:145], v[146:149], v[68:71], v[142:145]
	ds_read_b128 v[146:149], v119 offset:64
	ds_read_b128 v[150:153], v120
	ds_read_b128 v[154:157], v120 offset:64
	ds_read_b128 v[158:161], v121
	ds_read_b128 v[162:165], v121 offset:64
	v_cndmask_b32_e64 v100, v100, v134, s[6:7]
	s_waitcnt lgkmcnt(5)
	v_mfma_f32_16x16x32_bf16 v[138:141], v[138:141], v[72:75], 0
	v_readlane_b32 s6, v243, 14
	v_readlane_b32 s7, v243, 15
	v_mov_b32_e32 v218, s4
	s_waitcnt lgkmcnt(1)
	v_mfma_f32_16x16x32_bf16 v[158:161], v[158:161], v[72:75], 0
	v_mov_b32_e32 v220, s4
	v_mov_b32_e32 v222, s4
	v_readlane_b32 s5, v244, 11
	v_mfma_f32_16x16x32_bf16 v[138:141], v[146:149], v[68:71], v[138:141]
	ds_read_b128 v[146:149], v122
	ds_read_b128 v[166:169], v122 offset:64
	ds_read_b128 v[170:173], v123
	ds_read_b128 v[174:177], v123 offset:64
	ds_read_b128 v[196:199], v124
	ds_read_b128 v[200:203], v124 offset:64
	ds_read_b128 v[204:207], v125
	ds_read_b128 v[208:211], v125 offset:64
	v_readlane_b32 s8, v244, 14
	s_waitcnt lgkmcnt(8)
	v_mfma_f32_16x16x32_bf16 v[158:161], v[162:165], v[68:71], v[158:161]
	v_cndmask_b32_e64 v163, v184, v135, s[6:7]
	v_readlane_b32 s6, v243, 16
	v_readlane_b32 s7, v243, 17
	s_waitcnt lgkmcnt(7)
	v_mfma_f32_16x16x32_bf16 v[146:149], v[146:149], v[72:75], 0
	v_mov_b32_e32 v162, s4
	v_cndmask_b32_e64 v165, v184, v136, s[6:7]
	v_readlane_b32 s6, v243, 18
	v_readlane_b32 s7, v243, 19
	s_waitcnt lgkmcnt(6)
	v_mfma_f32_16x16x32_bf16 v[146:149], v[166:169], v[68:71], v[146:149]
	v_cndmask_b32_e64 v158, v162, v158, s[36:37]
	v_cndmask_b32_e64 v166, v184, v137, s[6:7]
	v_readlane_b32 s6, v243, 20
	v_readlane_b32 s7, v243, 21
	v_mfma_f32_16x16x32_bf16 v[150:153], v[150:153], v[72:75], 0
	v_cndmask_b32_e64 v159, v184, v159, s[38:39]
	v_cndmask_b32_e64 v167, v178, v142, s[6:7]
	v_readlane_b32 s6, v243, 22
	v_readlane_b32 s7, v243, 23
	v_mfma_f32_16x16x32_bf16 v[150:153], v[154:157], v[68:71], v[150:153]
	ds_read_b128 v[154:157], v126
	ds_read_b128 v[212:215], v126 offset:64
	v_cndmask_b32_e64 v168, v184, v143, s[6:7]
	v_readlane_b32 s6, v243, 24
	v_readlane_b32 s7, v243, 25
	s_waitcnt lgkmcnt(7)
	v_mfma_f32_16x16x32_bf16 v[134:137], v[170:173], v[72:75], 0
	v_cndmask_b32_e64 v171, v216, v138, s[0:1]
	v_cndmask_b32_e64 v169, v184, v144, s[6:7]
	v_readlane_b32 s6, v243, 26
	v_readlane_b32 s7, v243, 27
	s_waitcnt lgkmcnt(6)
	v_mfma_f32_16x16x32_bf16 v[134:137], v[174:177], v[68:71], v[134:137]
	v_cndmask_b32_e64 v172, v184, v139, s[20:21]
	v_cndmask_b32_e64 v170, v184, v145, s[6:7]
	v_cndmask_b32_e64 v173, v184, v140, s[22:23]
	s_waitcnt lgkmcnt(5)
	v_mfma_f32_16x16x32_bf16 v[142:145], v[196:199], v[72:75], 0
	v_cndmask_b32_e64 v174, v184, v141, s[24:25]
	v_cndmask_b32_e64 v150, v218, v150, s[26:27]
	v_cndmask_b32_e64 v151, v184, v151, s[28:29]
	s_waitcnt lgkmcnt(4)
	v_mfma_f32_16x16x32_bf16 v[138:141], v[200:203], v[68:71], v[142:145]
	v_cndmask_b32_e64 v152, v184, v152, s[30:31]
	v_cndmask_b32_e64 v153, v184, v153, s[34:35]
	v_mov_b32_e32 v164, s4
	s_waitcnt lgkmcnt(3)
	v_mfma_f32_16x16x32_bf16 v[142:145], v[204:207], v[72:75], 0
	v_cndmask_b32_e64 v160, v184, v160, s[40:41]
	v_cndmask_b32_e64 v161, v184, v161, s[42:43]
	v_cndmask_b32_e64 v146, v164, v146, s[44:45]
	s_waitcnt lgkmcnt(1)
	v_mfma_f32_16x16x32_bf16 v[72:75], v[154:157], v[72:75], 0
	v_cndmask_b32_e64 v147, v184, v147, s[46:47]
	v_cndmask_b32_e64 v148, v184, v148, s[48:49]
	v_cndmask_b32_e64 v149, v184, v149, s[50:51]
	v_mfma_f32_16x16x32_bf16 v[142:145], v[208:211], v[68:71], v[142:145]
	v_cndmask_b32_e64 v134, v220, v134, s[52:53]
	v_cndmask_b32_e64 v135, v184, v135, s[54:55]
	v_readlane_b32 s9, v244, 15
	s_waitcnt lgkmcnt(0)
	v_mfma_f32_16x16x32_bf16 v[68:71], v[212:215], v[68:71], v[72:75]
	v_readlane_b32 s10, v244, 16
	s_nop 1
	v_cndmask_b32_e64 v154, v184, v143, s[70:71]
	v_cndmask_b32_e64 v155, v184, v144, s[72:73]
	v_mov_b32_e32 v99, s94
	v_mul_f32_e32 v72, 0x3fb8aa3b, v99
	v_max3_f32 v72, v72, v100, v163
	v_max3_f32 v72, v72, v165, v166
	v_max3_f32 v72, v72, v167, v168
	v_max3_f32 v72, v72, v169, v170
	v_max3_f32 v72, v72, v171, v172
	v_max3_f32 v72, v72, v173, v174
	v_max3_f32 v72, v72, v150, v151
	v_max3_f32 v72, v72, v152, v153
	v_max3_f32 v72, v72, v158, v159
	v_max3_f32 v72, v72, v160, v161
	v_max3_f32 v72, v72, v146, v147
	v_max3_f32 v72, v72, v148, v149
	v_cndmask_b32_e64 v73, v184, v136, s[56:57]
	v_cndmask_b32_e64 v74, v184, v137, s[58:59]
	v_max3_f32 v72, v72, v134, v135
	v_cndmask_b32_e64 v75, v222, v138, s[60:61]
	v_cndmask_b32_e64 v136, v184, v139, s[62:63]
	v_max3_f32 v72, v72, v73, v74
	v_max3_f32 v72, v72, v75, v136
	v_cndmask_b32_e64 v137, v184, v140, s[64:65]
	v_cndmask_b32_e64 v138, v184, v141, s[66:67]
	v_max3_f32 v139, v72, v137, v138
	v_mov_b32_e32 v72, s4
	v_cndmask_b32_e64 v140, v72, v142, s[68:69]
	v_max3_f32 v72, v139, v140, v154
	v_cndmask_b32_e64 v162, v184, v145, s[74:75]
	v_max3_f32 v139, v72, v155, v162
	v_mov_b32_e32 v72, s4
	v_cndmask_b32_e64 v164, v72, v68, s[76:77]
	v_cndmask_b32_e64 v175, v184, v69, s[78:79]
	v_max3_f32 v68, v139, v164, v175
	v_cndmask_b32_e64 v176, v184, v70, s[80:81]
	v_cndmask_b32_e64 v177, v184, v71, s[82:83]
	v_max3_f32 v68, v68, v176, v177
	v_mov_b32_e32 v69, v68
	s_nop 1
	v_permlane16_swap_b32 v69, v68
	s_mov_b32 s4, 0x3fb8aa3b
	v_readlane_b32 s11, v244, 17
	v_readlane_b32 s12, v244, 18
	v_readlane_b32 s13, v244, 19
	s_waitcnt lgkmcnt(0)
	v_max_f32_e32 v69, v69, v69
	v_max_f32_e32 v68, v68, v69
	v_mov_b32_e32 v69, v68
	s_nop 1
	v_permlane32_swap_b32 v69, v68
	v_readlane_b32 s14, v244, 20
	v_readlane_b32 s15, v244, 21
	v_readlane_b32 s18, v244, 24
	v_readlane_b32 s19, v244, 25
	s_waitcnt lgkmcnt(0)
	v_max_f32_e32 v69, v69, v69
	v_max_f32_e32 v178, v68, v69
	v_sub_f32_e32 v68, v100, v178
	v_exp_f32_e32 v72, v68
	v_sub_f32_e32 v68, v163, v178
	v_exp_f32_e32 v100, v68
	v_sub_f32_e32 v69, v165, v178
	v_exp_f32_e32 v139, v69
	v_sub_f32_e32 v69, v166, v178
	v_exp_f32_e32 v141, v69
	v_sub_f32_e32 v69, v167, v178
	v_add_f32_e32 v68, 0, v72
	v_exp_f32_e32 v142, v69
	v_sub_f32_e32 v69, v168, v178
	v_add_f32_e32 v68, v100, v68
	v_exp_f32_e32 v143, v69
	v_sub_f32_e32 v69, v169, v178
	v_add_f32_e32 v68, v139, v68
	v_exp_f32_e32 v144, v69
	v_sub_f32_e32 v69, v170, v178
	v_add_f32_e32 v68, v141, v68
	v_exp_f32_e32 v145, v69
	v_sub_f32_e32 v69, v171, v178
	v_add_f32_e32 v68, v142, v68
	v_exp_f32_e32 v156, v69
	v_sub_f32_e32 v69, v172, v178
	v_add_f32_e32 v68, v143, v68
	v_exp_f32_e32 v157, v69
	v_sub_f32_e32 v69, v173, v178
	v_add_f32_e32 v68, v144, v68
	v_exp_f32_e32 v163, v69
	v_sub_f32_e32 v69, v174, v178
	v_add_f32_e32 v68, v145, v68
	v_exp_f32_e32 v165, v69
	v_sub_f32_e32 v69, v150, v178
	v_add_f32_e32 v68, v156, v68
	v_exp_f32_e32 v166, v69
	v_sub_f32_e32 v69, v151, v178
	v_add_f32_e32 v68, v157, v68
	v_exp_f32_e32 v167, v69
	v_sub_f32_e32 v69, v152, v178
	v_add_f32_e32 v68, v163, v68
	v_exp_f32_e32 v168, v69
	v_sub_f32_e32 v69, v153, v178
	v_add_f32_e32 v68, v165, v68
	v_exp_f32_e32 v169, v69
	v_sub_f32_e32 v69, v158, v178
	v_add_f32_e32 v68, v166, v68
	v_exp_f32_e32 v158, v69
	v_sub_f32_e32 v69, v159, v178
	v_add_f32_e32 v68, v167, v68
	v_exp_f32_e32 v159, v69
	v_sub_f32_e32 v69, v160, v178
	v_add_f32_e32 v68, v168, v68
	v_exp_f32_e32 v160, v69
	v_sub_f32_e32 v69, v161, v178
	v_add_f32_e32 v68, v169, v68
	v_exp_f32_e32 v161, v69
	v_sub_f32_e32 v69, v146, v178
	v_add_f32_e32 v68, v158, v68
	v_exp_f32_e32 v170, v69
	v_sub_f32_e32 v69, v147, v178
	v_add_f32_e32 v68, v159, v68
	v_exp_f32_e32 v171, v69
	v_sub_f32_e32 v69, v148, v178
	v_add_f32_e32 v68, v160, v68
	v_exp_f32_e32 v172, v69
	v_sub_f32_e32 v69, v149, v178
	v_add_f32_e32 v68, v161, v68
	v_exp_f32_e32 v173, v69
	v_sub_f32_e32 v69, v134, v178
	v_add_f32_e32 v68, v170, v68
	v_exp_f32_e32 v174, v69
	v_sub_f32_e32 v69, v135, v178
	v_add_f32_e32 v68, v171, v68
	v_exp_f32_e32 v179, v69
	v_sub_f32_e32 v69, v73, v178
	v_add_f32_e32 v68, v172, v68
	v_exp_f32_e32 v195, v69
	v_sub_f32_e32 v69, v74, v178
	v_add_f32_e32 v68, v173, v68
	v_exp_f32_e32 v196, v69
	v_sub_f32_e32 v69, v75, v178
	v_add_f32_e32 v68, v174, v68
	v_exp_f32_e32 v197, v69
	v_sub_f32_e32 v69, v136, v178
	v_add_f32_e32 v68, v179, v68
	v_exp_f32_e32 v198, v69
	v_add_f32_e32 v68, v195, v68
	v_add_f32_e32 v68, v196, v68
	v_add_f32_e32 v68, v197, v68
	v_add_f32_e32 v146, v198, v68
	v_sub_f32_e32 v68, v137, v178
	v_exp_f32_e32 v199, v68
	v_sub_f32_e32 v68, v138, v178
	v_add_u32_e32 v74, 0xb000, v127
	v_exp_f32_e32 v200, v68
	v_add_u32_e32 v68, 0x9000, v127
	v_cvt_pk_bf16_f32 v72, v72, v100
	ds_read_b128 v[134:137], v74 offset:256
	v_cvt_pk_bf16_f32 v74, v142, v143
	v_add_u32_e32 v100, 0xd000, v127
	v_add_u32_e32 v142, 0xf000, v127
	v_sub_f32_e32 v147, v140, v178
	ds_read_b128 v[68:71], v68
	v_cvt_pk_bf16_f32 v73, v139, v141
	v_cvt_pk_bf16_f32 v75, v144, v145
	ds_read_b128 v[138:141], v100 offset:512
	ds_read_b128 v[142:145], v142 offset:768
	s_waitcnt lgkmcnt(2)
	v_mfma_f32_16x16x32_bf16 v[68:71], v[68:71], v[72:75], 0
	v_exp_f32_e32 v100, v147
	v_add_f32_e32 v146, v199, v146
	v_add_f32_e32 v146, v200, v146
	v_mfma_f32_16x16x32_bf16 v[134:137], v[134:137], v[72:75], 0
	v_add_f32_e32 v201, v100, v146
	v_sub_f32_e32 v146, v154, v178
	v_add_u32_e32 v148, 0xb000, v130
	s_waitcnt lgkmcnt(1)
	v_mfma_f32_16x16x32_bf16 v[138:141], v[138:141], v[72:75], 0
	v_exp_f32_e32 v202, v146
	v_cvt_pk_bf16_f32 v146, v156, v157
	v_cvt_pk_bf16_f32 v147, v163, v165
	s_waitcnt lgkmcnt(0)
	v_mfma_f32_16x16x32_bf16 v[72:75], v[142:145], v[72:75], 0
	v_add_u32_e32 v142, 0x9000, v130
	ds_read_b128 v[142:145], v142
	ds_read_b128 v[150:153], v148 offset:256
	v_cvt_pk_bf16_f32 v148, v166, v167
	v_cvt_pk_bf16_f32 v149, v168, v169
	v_add_u32_e32 v154, 0xd000, v130
	s_waitcnt lgkmcnt(1)
	v_mfma_f32_16x16x32_bf16 v[68:71], v[142:145], v[146:149], v[68:71]
	v_add_u32_e32 v142, 0xf000, v130
	ds_read_b128 v[142:145], v142 offset:768
	v_sub_f32_e32 v203, v155, v178
	ds_read_b128 v[154:157], v154 offset:512
	s_waitcnt lgkmcnt(1)
	v_mfma_f32_16x16x32_bf16 v[72:75], v[142:145], v[146:149], v[72:75]
	v_add_u32_e32 v142, 0x9000, v131
	ds_read_b128 v[142:145], v142
	v_exp_f32_e32 v163, v203
	v_mfma_f32_16x16x32_bf16 v[134:137], v[150:153], v[146:149], v[134:137]
	v_sub_f32_e32 v150, v162, v178
	v_exp_f32_e32 v162, v150
	v_add_f32_e32 v150, v202, v201
	s_waitcnt lgkmcnt(1)
	v_mfma_f32_16x16x32_bf16 v[138:141], v[154:157], v[146:149], v[138:141]
	v_add_f32_e32 v150, v163, v150
	v_add_u32_e32 v148, 0xb000, v131
	v_add_f32_e32 v165, v162, v150
	v_cvt_pk_bf16_f32 v146, v158, v159
	v_cvt_pk_bf16_f32 v147, v160, v161
	ds_read_b128 v[150:153], v148 offset:256
	v_cvt_pk_bf16_f32 v148, v170, v171
	v_cvt_pk_bf16_f32 v149, v172, v173
	v_add_u32_e32 v154, 0xd000, v131
	s_waitcnt lgkmcnt(1)
	v_mfma_f32_16x16x32_bf16 v[68:71], v[142:145], v[146:149], v[68:71]
	v_add_u32_e32 v142, 0xf000, v131
	ds_read_b128 v[142:145], v142 offset:768
	ds_read_b128 v[154:157], v154 offset:512
	s_waitcnt lgkmcnt(1)
	v_mfma_f32_16x16x32_bf16 v[72:75], v[142:145], v[146:149], v[72:75]
	v_add_u32_e32 v142, 0x9000, v132
	ds_read_b128 v[142:145], v142
	v_sub_f32_e32 v164, v164, v178
	v_mfma_f32_16x16x32_bf16 v[134:137], v[150:153], v[146:149], v[134:137]
	v_sub_f32_e32 v150, v175, v178
	v_exp_f32_e32 v160, v150
	v_sub_f32_e32 v150, v176, v178
	s_waitcnt lgkmcnt(1)
	v_mfma_f32_16x16x32_bf16 v[138:141], v[154:157], v[146:149], v[138:141]
	v_add_u32_e32 v148, 0xb000, v132
	v_exp_f32_e32 v161, v150
	ds_read_b128 v[150:153], v148 offset:256
	v_exp_f32_e32 v158, v164
	v_sub_f32_e32 v164, v177, v178
	v_exp_f32_e32 v164, v164
	v_cvt_pk_bf16_f32 v146, v174, v179
	v_add_f32_e32 v159, v158, v165
	v_cvt_pk_bf16_f32 v147, v195, v196
	v_cvt_pk_bf16_f32 v148, v197, v198
	v_cvt_pk_bf16_f32 v149, v199, v200
	v_add_u32_e32 v154, 0xd000, v132
	s_waitcnt lgkmcnt(1)
	v_mfma_f32_16x16x32_bf16 v[68:71], v[142:145], v[146:149], v[68:71]
	v_add_f32_e32 v142, v160, v159
	v_add_f32_e32 v142, v161, v142
	ds_read_b128 v[154:157], v154 offset:512
	s_waitcnt lgkmcnt(1)
	v_mfma_f32_16x16x32_bf16 v[134:137], v[150:153], v[146:149], v[134:137]
	v_add_f32_e32 v150, v164, v142
	v_add_u32_e32 v142, 0xf000, v132
	ds_read_b128 v[142:145], v142 offset:768
	ds_bpermute_b32 v151, v128, v150
	s_waitcnt lgkmcnt(1)
	v_mfma_f32_16x16x32_bf16 v[72:75], v[142:145], v[146:149], v[72:75]
	v_add_u32_e32 v142, 0x9000, v133
	ds_read_b128 v[142:145], v142
	s_waitcnt lgkmcnt(1)
	v_add_f32_e32 v159, v150, v151
	v_mfma_f32_16x16x32_bf16 v[138:141], v[154:157], v[146:149], v[138:141]
	ds_bpermute_b32 v165, v113, v159
	v_cvt_pk_bf16_f32 v146, v100, v202
	v_add_u32_e32 v100, 0xb000, v133
	ds_read_b128 v[150:153], v100 offset:256
	v_add_u32_e32 v100, 0xd000, v133
	v_fma_f32 v99, v99, s4, -v178
	ds_read_b128 v[154:157], v100 offset:512
	v_add_u32_e32 v100, 0xf000, v133
	v_exp_f32_e32 v99, v99
	v_cvt_pk_bf16_f32 v147, v163, v162
	v_cvt_pk_bf16_f32 v148, v158, v160
	v_cvt_pk_bf16_f32 v149, v161, v164
	v_writelane_b32 v244, s90, 62
	s_waitcnt lgkmcnt(3)
	v_mfma_f32_16x16x32_bf16 v[68:71], v[142:145], v[146:149], v[68:71]
	ds_read_b128 v[142:145], v100 offset:768
	s_waitcnt lgkmcnt(3)
	v_add_f32_e32 v100, v159, v165
	v_add_f32_e32 v99, v99, v100
	v_rcp_f32_e32 v100, v99
	s_waitcnt lgkmcnt(2)
	v_mfma_f32_16x16x32_bf16 v[134:137], v[150:153], v[146:149], v[134:137]
	v_lshl_add_u32 v99, s90, 7, v109
	s_mov_b32 s16, 0xf149f2ca
	v_pk_mul_f32 v[70:71], v[70:71], v[100:101] op_sel_hi:[1,0]
	s_waitcnt lgkmcnt(1)
	v_mfma_f32_16x16x32_bf16 v[138:141], v[154:157], v[146:149], v[138:141]
	v_mul_f32_e64 v68, v68, v100
	v_mul_f32_e64 v69, v69, v100
	s_nop 0
	v_pk_mul_f32 v[134:135], v[134:135], v[100:101] op_sel_hi:[1,0]
	v_writelane_b32 v244, s91, 63
	s_waitcnt lgkmcnt(0)
	v_mfma_f32_16x16x32_bf16 v[72:75], v[142:145], v[146:149], v[72:75]
	v_mul_f32_e64 v142, v70, v70
	v_mul_f32_e64 v143, v71, v71
	v_pk_mul_f32 v[144:145], v[68:69], v[68:69]
	v_cvt_pk_bf16_f32 v68, v68, v69
	v_cvt_pk_bf16_f32 v69, v70, v71
	v_pk_mul_f32 v[70:71], v[136:137], v[100:101] op_sel_hi:[1,0]
	v_pk_mov_b32 v[146:147], v[144:145], v[142:143] op_sel:[1,0]
	v_mov_b32_e32 v145, v143
	v_pk_add_f32 v[142:143], v[146:147], v[144:145]
	v_pk_mul_f32 v[136:137], v[70:71], v[70:71]
	v_add_f32_e32 v142, v142, v143
	v_pk_mul_f32 v[144:145], v[134:135], v[134:135]
	v_cvt_pk_bf16_f32 v134, v134, v135
	v_cvt_pk_bf16_f32 v135, v70, v71
	v_pk_mul_f32 v[70:71], v[138:139], v[100:101] op_sel_hi:[1,0]
	v_add_f32_e32 v143, v110, v142
	v_pk_mov_b32 v[146:147], v[144:145], v[136:137] op_sel:[1,0]
	v_mov_b32_e32 v145, v137
	ds_write2_b64 v99, v[68:69], v[134:135] offset1:4
	v_pk_mul_f32 v[68:69], v[140:141], v[100:101] op_sel_hi:[1,0]
	v_mul_f32_e32 v110, v70, v70
	v_pk_add_f32 v[136:137], v[146:147], v[144:145]
	v_pk_fma_f32 v[134:135], v[70:71], v[70:71], v[110:111] op_sel_hi:[1,1,0]
	v_mul_f32_e32 v110, v68, v68
	v_pk_add_f32 v[136:137], v[136:137], v[136:137] op_sel_hi:[0,1]
	v_pk_fma_f32 v[138:139], v[68:69], v[68:69], v[110:111] op_sel_hi:[1,1,0]
	v_cvt_pk_bf16_f32 v70, v70, v71
	v_cvt_pk_bf16_f32 v71, v68, v69
	v_pk_mul_f32 v[68:69], v[74:75], v[100:101] op_sel_hi:[1,0]
	v_pk_mul_f32 v[72:73], v[72:73], v[100:101] op_sel_hi:[1,0]
	v_mul_f32_e32 v136, v68, v68
	v_mul_f32_e32 v134, v72, v72
	v_mul_f32_e32 v138, v73, v73
	v_mul_f32_e32 v142, v69, v69
	v_pk_add_f32 v[74:75], v[134:135], v[138:139]
	v_pk_add_f32 v[134:135], v[136:137], v[142:143]
	s_and_b64 vcc, exec, s[2:3]
	v_pk_add_f32 v[74:75], v[74:75], v[134:135]
	s_mov_b32 s90, 1
	v_add_f32_e32 v110, v74, v75
	s_mov_b64 s[2:3], 0
	v_cvt_pk_bf16_f32 v72, v72, v73
	v_cvt_pk_bf16_f32 v73, v68, v69
	ds_write2_b64 v99, v[70:71], v[72:73] offset0:8 offset1:12
	s_cbranch_vccnz .LBB0_181
